# NSA top-2 block selection: branch-free compare/select, importance rows read in chunks ahead of use
# speedup vs baseline: 1.0065x; 1.0024x over previous
; DI void nsa_attn_phase(const int tid0, LAS unsigned char* lds, const P& p, int G, int c) {
;     ...
;         if (tid < 64) { unsigned mask;
;             if (i <= 3) mask = (1u << (i + 1)) - 1u;
;             else { float v1 = -1.f, v2 = -1.f; int n1 = 0, n2 = 0;
;                 for (int n = 1; n < i; ++n) { const float v = ((imp4[(0 * 64 + tid) * 33 + n] + imp4[(1 * 64 + tid) * 33 + n]) + imp4[(2 * 64 + tid) * 33 + n]) + imp4[(3 * 64 + tid) * 33 + n];
;                     if (v > v1) { v2 = v1; n2 = n1; v1 = v; n1 = n; } else if (v > v2) { v2 = v; n2 = n; } }
;                 mask = 1u | (1u << i) | (1u << n1) | (1u << n2); }
;             selm[tid] = mask; }
.LBB0_215:
	v_cmp_gt_i32_e32 vcc, 64, v74
	s_barrier
	s_and_saveexec_b64 s[0:1], vcc
	s_cbranch_execz .LBB0_234
	s_cmp_gt_i32 s41, 27
	s_mov_b64 s[4:5], -1
	s_cbranch_scc1 .LBB0_231
	s_movk_i32 s4, 0x84
	v_mul_lo_u32 v0, v74, s4
	v_readlane_b32 s4, v253, 49
	s_sub_i32 s8, 30, s41
	v_mov_b32_e32 v2, 0
	v_mov_b32_e32 v1, -1.0
	v_mov_b32_e32 v3, -1.0
	v_mov_b32_e32 v4, 0
	v_add_u32_e32 v0, s4, v0
	ds_read2st64_b32 v[114:115], v0 offset1:33
	ds_read2st64_b32 v[116:117], v0 offset0:66 offset1:99
	v_add_u32_e32 v139, 4, v0
	ds_read2st64_b32 v[118:119], v139 offset1:33
	ds_read2st64_b32 v[120:121], v139 offset0:66 offset1:99
	v_add_u32_e32 v140, 8, v0
	ds_read2st64_b32 v[122:123], v140 offset1:33
	ds_read2st64_b32 v[124:125], v140 offset0:66 offset1:99
	v_add_u32_e32 v138, 12, v0
	ds_read2st64_b32 v[126:127], v138 offset1:33
	ds_read2st64_b32 v[128:129], v138 offset0:66 offset1:99
	v_add_u32_e32 v139, 16, v0
	ds_read2st64_b32 v[130:131], v139 offset1:33
	ds_read2st64_b32 v[132:133], v139 offset0:66 offset1:99
	v_add_u32_e32 v140, 20, v0
	ds_read2st64_b32 v[134:135], v140 offset1:33
	ds_read2st64_b32 v[136:137], v140 offset0:66 offset1:99
	s_waitcnt lgkmcnt(6)
	v_add_f32_e32 v144, v114, v115
	v_add_f32_e32 v145, v118, v119
	v_add_f32_e32 v146, v122, v123
	v_add_f32_e32 v144, v144, v116
	v_add_f32_e32 v145, v145, v120
	v_add_f32_e32 v146, v146, v124
	v_add_f32_e32 v144, v144, v117
	v_add_f32_e32 v145, v145, v121
	v_add_f32_e32 v146, v146, v125
	v_add_u32_e32 v138, 24, v0
	ds_read2st64_b32 v[114:115], v138 offset1:33
	ds_read2st64_b32 v[116:117], v138 offset0:66 offset1:99
	v_add_u32_e32 v139, 28, v0
	ds_read2st64_b32 v[118:119], v139 offset1:33
	ds_read2st64_b32 v[120:121], v139 offset0:66 offset1:99
	v_add_u32_e32 v140, 32, v0
	ds_read2st64_b32 v[122:123], v140 offset1:33
	ds_read2st64_b32 v[124:125], v140 offset0:66 offset1:99
	v_cmp_gt_f32_e64 s[4:5], v144, v3
	v_cmp_gt_f32_e32 vcc, v144, v1
	s_nop 0
	v_cndmask_b32_e64 v4, v4, 1, s[4:5]
	v_cndmask_b32_e64 v3, v3, v144, s[4:5]
	v_cndmask_b32_e32 v4, v4, v2, vcc
	v_cndmask_b32_e32 v3, v3, v1, vcc
	v_cndmask_b32_e64 v2, v2, 1, vcc
	v_cndmask_b32_e32 v1, v1, v144, vcc
	s_cmp_eq_u32 s8, 1
	s_cbranch_scc1 .Ltopk_done
	v_cmp_gt_f32_e64 s[4:5], v145, v3
	v_cmp_gt_f32_e32 vcc, v145, v1
	s_nop 0
	v_cndmask_b32_e64 v4, v4, 2, s[4:5]
	v_cndmask_b32_e64 v3, v3, v145, s[4:5]
	v_cndmask_b32_e32 v4, v4, v2, vcc
	v_cndmask_b32_e32 v3, v3, v1, vcc
	v_cndmask_b32_e64 v2, v2, 2, vcc
	v_cndmask_b32_e32 v1, v1, v145, vcc
	s_cmp_eq_u32 s8, 2
	s_cbranch_scc1 .Ltopk_done
	v_cmp_gt_f32_e64 s[4:5], v146, v3
	v_cmp_gt_f32_e32 vcc, v146, v1
	s_nop 0
	v_cndmask_b32_e64 v4, v4, 3, s[4:5]
	v_cndmask_b32_e64 v3, v3, v146, s[4:5]
	v_cndmask_b32_e32 v4, v4, v2, vcc
	v_cndmask_b32_e32 v3, v3, v1, vcc
	v_cndmask_b32_e64 v2, v2, 3, vcc
	v_cndmask_b32_e32 v1, v1, v146, vcc
	s_cmp_eq_u32 s8, 3
	s_cbranch_scc1 .Ltopk_done
	s_waitcnt lgkmcnt(6)
	v_add_f32_e32 v144, v126, v127
	v_add_f32_e32 v145, v130, v131
	v_add_f32_e32 v146, v134, v135
	v_add_f32_e32 v144, v144, v128
	v_add_f32_e32 v145, v145, v132
	v_add_f32_e32 v146, v146, v136
	v_add_f32_e32 v144, v144, v129
	v_add_f32_e32 v145, v145, v133
	v_add_f32_e32 v146, v146, v137
	v_add_u32_e32 v138, 36, v0
	ds_read2st64_b32 v[126:127], v138 offset1:33
	ds_read2st64_b32 v[128:129], v138 offset0:66 offset1:99
	v_add_u32_e32 v139, 40, v0
	ds_read2st64_b32 v[130:131], v139 offset1:33
	ds_read2st64_b32 v[132:133], v139 offset0:66 offset1:99
	v_add_u32_e32 v140, 44, v0
	ds_read2st64_b32 v[134:135], v140 offset1:33
	ds_read2st64_b32 v[136:137], v140 offset0:66 offset1:99
	v_cmp_gt_f32_e64 s[4:5], v144, v3
	v_cmp_gt_f32_e32 vcc, v144, v1
	s_nop 0
	v_cndmask_b32_e64 v4, v4, 4, s[4:5]
	v_cndmask_b32_e64 v3, v3, v144, s[4:5]
	v_cndmask_b32_e32 v4, v4, v2, vcc
	v_cndmask_b32_e32 v3, v3, v1, vcc
	v_cndmask_b32_e64 v2, v2, 4, vcc
	v_cndmask_b32_e32 v1, v1, v144, vcc
	s_cmp_eq_u32 s8, 4
	s_cbranch_scc1 .Ltopk_done
	v_cmp_gt_f32_e64 s[4:5], v145, v3
	v_cmp_gt_f32_e32 vcc, v145, v1
	s_nop 0
	v_cndmask_b32_e64 v4, v4, 5, s[4:5]
	v_cndmask_b32_e64 v3, v3, v145, s[4:5]
	v_cndmask_b32_e32 v4, v4, v2, vcc
	v_cndmask_b32_e32 v3, v3, v1, vcc
	v_cndmask_b32_e64 v2, v2, 5, vcc
	v_cndmask_b32_e32 v1, v1, v145, vcc
	s_cmp_eq_u32 s8, 5
	s_cbranch_scc1 .Ltopk_done
	v_cmp_gt_f32_e64 s[4:5], v146, v3
	v_cmp_gt_f32_e32 vcc, v146, v1
	s_nop 0
	v_cndmask_b32_e64 v4, v4, 6, s[4:5]
	v_cndmask_b32_e64 v3, v3, v146, s[4:5]
	v_cndmask_b32_e32 v4, v4, v2, vcc
	v_cndmask_b32_e32 v3, v3, v1, vcc
	v_cndmask_b32_e64 v2, v2, 6, vcc
	v_cndmask_b32_e32 v1, v1, v146, vcc
	s_cmp_eq_u32 s8, 6
	s_cbranch_scc1 .Ltopk_done
	s_waitcnt lgkmcnt(6)
	v_add_f32_e32 v144, v114, v115
	v_add_f32_e32 v145, v118, v119
	v_add_f32_e32 v146, v122, v123
	v_add_f32_e32 v144, v144, v116
	v_add_f32_e32 v145, v145, v120
	v_add_f32_e32 v146, v146, v124
	v_add_f32_e32 v144, v144, v117
	v_add_f32_e32 v145, v145, v121
	v_add_f32_e32 v146, v146, v125
	v_add_u32_e32 v138, 48, v0
	ds_read2st64_b32 v[114:115], v138 offset1:33
	ds_read2st64_b32 v[116:117], v138 offset0:66 offset1:99
	v_add_u32_e32 v139, 52, v0
	ds_read2st64_b32 v[118:119], v139 offset1:33
	ds_read2st64_b32 v[120:121], v139 offset0:66 offset1:99
	v_add_u32_e32 v140, 56, v0
	ds_read2st64_b32 v[122:123], v140 offset1:33
	ds_read2st64_b32 v[124:125], v140 offset0:66 offset1:99
	v_cmp_gt_f32_e64 s[4:5], v144, v3
	v_cmp_gt_f32_e32 vcc, v144, v1
	s_nop 0
	v_cndmask_b32_e64 v4, v4, 7, s[4:5]
	v_cndmask_b32_e64 v3, v3, v144, s[4:5]
	v_cndmask_b32_e32 v4, v4, v2, vcc
	v_cndmask_b32_e32 v3, v3, v1, vcc
	v_cndmask_b32_e64 v2, v2, 7, vcc
	v_cndmask_b32_e32 v1, v1, v144, vcc
	s_cmp_eq_u32 s8, 7
	s_cbranch_scc1 .Ltopk_done
; DI void nsa_attn_phase(const int tid0, LAS unsigned char* lds, const P& p, int G, int c) {
;     ...
;         if (tid < 64) { unsigned mask;
;             if (i <= 3) mask = (1u << (i + 1)) - 1u;
;             else { float v1 = -1.f, v2 = -1.f; int n1 = 0, n2 = 0;
;                 for (int n = 1; n < i; ++n) { const float v = ((imp4[(0 * 64 + tid) * 33 + n] + imp4[(1 * 64 + tid) * 33 + n]) + imp4[(2 * 64 + tid) * 33 + n]) + imp4[(3 * 64 + tid) * 33 + n];
;                     if (v > v1) { v2 = v1; n2 = n1; v1 = v; n1 = n; } else if (v > v2) { v2 = v; n2 = n; } }
;                 mask = 1u | (1u << i) | (1u << n1) | (1u << n2); }
;             selm[tid] = mask; }
	v_cmp_gt_f32_e64 s[4:5], v145, v3
	v_cmp_gt_f32_e32 vcc, v145, v1
	s_nop 0
	v_cndmask_b32_e64 v4, v4, 8, s[4:5]
	v_cndmask_b32_e64 v3, v3, v145, s[4:5]
	v_cndmask_b32_e32 v4, v4, v2, vcc
	v_cndmask_b32_e32 v3, v3, v1, vcc
	v_cndmask_b32_e64 v2, v2, 8, vcc
	v_cndmask_b32_e32 v1, v1, v145, vcc
	s_cmp_eq_u32 s8, 8
	s_cbranch_scc1 .Ltopk_done
	v_cmp_gt_f32_e64 s[4:5], v146, v3
	v_cmp_gt_f32_e32 vcc, v146, v1
	s_nop 0
	v_cndmask_b32_e64 v4, v4, 9, s[4:5]
	v_cndmask_b32_e64 v3, v3, v146, s[4:5]
	v_cndmask_b32_e32 v4, v4, v2, vcc
	v_cndmask_b32_e32 v3, v3, v1, vcc
	v_cndmask_b32_e64 v2, v2, 9, vcc
	v_cndmask_b32_e32 v1, v1, v146, vcc
	s_cmp_eq_u32 s8, 9
	s_cbranch_scc1 .Ltopk_done
	s_waitcnt lgkmcnt(6)
	v_add_f32_e32 v144, v126, v127
	v_add_f32_e32 v145, v130, v131
	v_add_f32_e32 v146, v134, v135
	v_add_f32_e32 v144, v144, v128
	v_add_f32_e32 v145, v145, v132
	v_add_f32_e32 v146, v146, v136
	v_add_f32_e32 v144, v144, v129
	v_add_f32_e32 v145, v145, v133
	v_add_f32_e32 v146, v146, v137
	v_add_u32_e32 v138, 60, v0
	ds_read2st64_b32 v[126:127], v138 offset1:33
	ds_read2st64_b32 v[128:129], v138 offset0:66 offset1:99
	v_add_u32_e32 v139, 64, v0
	ds_read2st64_b32 v[130:131], v139 offset1:33
	ds_read2st64_b32 v[132:133], v139 offset0:66 offset1:99
	v_add_u32_e32 v140, 68, v0
	ds_read2st64_b32 v[134:135], v140 offset1:33
	ds_read2st64_b32 v[136:137], v140 offset0:66 offset1:99
	v_cmp_gt_f32_e64 s[4:5], v144, v3
	v_cmp_gt_f32_e32 vcc, v144, v1
	s_nop 0
	v_cndmask_b32_e64 v4, v4, 10, s[4:5]
	v_cndmask_b32_e64 v3, v3, v144, s[4:5]
	v_cndmask_b32_e32 v4, v4, v2, vcc
	v_cndmask_b32_e32 v3, v3, v1, vcc
	v_cndmask_b32_e64 v2, v2, 10, vcc
	v_cndmask_b32_e32 v1, v1, v144, vcc
	s_cmp_eq_u32 s8, 10
	s_cbranch_scc1 .Ltopk_done
	v_cmp_gt_f32_e64 s[4:5], v145, v3
	v_cmp_gt_f32_e32 vcc, v145, v1
	s_nop 0
	v_cndmask_b32_e64 v4, v4, 11, s[4:5]
	v_cndmask_b32_e64 v3, v3, v145, s[4:5]
	v_cndmask_b32_e32 v4, v4, v2, vcc
	v_cndmask_b32_e32 v3, v3, v1, vcc
	v_cndmask_b32_e64 v2, v2, 11, vcc
	v_cndmask_b32_e32 v1, v1, v145, vcc
	s_cmp_eq_u32 s8, 11
	s_cbranch_scc1 .Ltopk_done
	v_cmp_gt_f32_e64 s[4:5], v146, v3
	v_cmp_gt_f32_e32 vcc, v146, v1
	s_nop 0
	v_cndmask_b32_e64 v4, v4, 12, s[4:5]
	v_cndmask_b32_e64 v3, v3, v146, s[4:5]
	v_cndmask_b32_e32 v4, v4, v2, vcc
	v_cndmask_b32_e32 v3, v3, v1, vcc
	v_cndmask_b32_e64 v2, v2, 12, vcc
	v_cndmask_b32_e32 v1, v1, v146, vcc
	s_cmp_eq_u32 s8, 12
	s_cbranch_scc1 .Ltopk_done
	s_waitcnt lgkmcnt(6)
	v_add_f32_e32 v144, v114, v115
	v_add_f32_e32 v145, v118, v119
	v_add_f32_e32 v146, v122, v123
	v_add_f32_e32 v144, v144, v116
	v_add_f32_e32 v145, v145, v120
	v_add_f32_e32 v146, v146, v124
	v_add_f32_e32 v144, v144, v117
	v_add_f32_e32 v145, v145, v121
	v_add_f32_e32 v146, v146, v125
	v_add_u32_e32 v138, 72, v0
	ds_read2st64_b32 v[114:115], v138 offset1:33
	ds_read2st64_b32 v[116:117], v138 offset0:66 offset1:99
	v_add_u32_e32 v139, 76, v0
	ds_read2st64_b32 v[118:119], v139 offset1:33
	ds_read2st64_b32 v[120:121], v139 offset0:66 offset1:99
	v_add_u32_e32 v140, 80, v0
	ds_read2st64_b32 v[122:123], v140 offset1:33
	ds_read2st64_b32 v[124:125], v140 offset0:66 offset1:99
	v_cmp_gt_f32_e64 s[4:5], v144, v3
	v_cmp_gt_f32_e32 vcc, v144, v1
	s_nop 0
	v_cndmask_b32_e64 v4, v4, 13, s[4:5]
	v_cndmask_b32_e64 v3, v3, v144, s[4:5]
	v_cndmask_b32_e32 v4, v4, v2, vcc
	v_cndmask_b32_e32 v3, v3, v1, vcc
	v_cndmask_b32_e64 v2, v2, 13, vcc
	v_cndmask_b32_e32 v1, v1, v144, vcc
	s_cmp_eq_u32 s8, 13
	s_cbranch_scc1 .Ltopk_done
	v_cmp_gt_f32_e64 s[4:5], v145, v3
	v_cmp_gt_f32_e32 vcc, v145, v1
	s_nop 0
	v_cndmask_b32_e64 v4, v4, 14, s[4:5]
	v_cndmask_b32_e64 v3, v3, v145, s[4:5]
	v_cndmask_b32_e32 v4, v4, v2, vcc
	v_cndmask_b32_e32 v3, v3, v1, vcc
	v_cndmask_b32_e64 v2, v2, 14, vcc
	v_cndmask_b32_e32 v1, v1, v145, vcc
	s_cmp_eq_u32 s8, 14
	s_cbranch_scc1 .Ltopk_done
	v_cmp_gt_f32_e64 s[4:5], v146, v3
	v_cmp_gt_f32_e32 vcc, v146, v1
	s_nop 0
	v_cndmask_b32_e64 v4, v4, 15, s[4:5]
	v_cndmask_b32_e64 v3, v3, v146, s[4:5]
	v_cndmask_b32_e32 v4, v4, v2, vcc
	v_cndmask_b32_e32 v3, v3, v1, vcc
	v_cndmask_b32_e64 v2, v2, 15, vcc
	v_cndmask_b32_e32 v1, v1, v146, vcc
	s_cmp_eq_u32 s8, 15
	s_cbranch_scc1 .Ltopk_done
	s_waitcnt lgkmcnt(6)
	v_add_f32_e32 v144, v126, v127
	v_add_f32_e32 v145, v130, v131
	v_add_f32_e32 v146, v134, v135
	v_add_f32_e32 v144, v144, v128
	v_add_f32_e32 v145, v145, v132
	v_add_f32_e32 v146, v146, v136
	v_add_f32_e32 v144, v144, v129
	v_add_f32_e32 v145, v145, v133
	v_add_f32_e32 v146, v146, v137
	v_add_u32_e32 v138, 84, v0
	ds_read2st64_b32 v[126:127], v138 offset1:33
	ds_read2st64_b32 v[128:129], v138 offset0:66 offset1:99
	v_add_u32_e32 v139, 88, v0
	ds_read2st64_b32 v[130:131], v139 offset1:33
	ds_read2st64_b32 v[132:133], v139 offset0:66 offset1:99
	v_add_u32_e32 v140, 92, v0
	ds_read2st64_b32 v[134:135], v140 offset1:33
	ds_read2st64_b32 v[136:137], v140 offset0:66 offset1:99
	v_cmp_gt_f32_e64 s[4:5], v144, v3
	v_cmp_gt_f32_e32 vcc, v144, v1
	s_nop 0
	v_cndmask_b32_e64 v4, v4, 16, s[4:5]
	v_cndmask_b32_e64 v3, v3, v144, s[4:5]
	v_cndmask_b32_e32 v4, v4, v2, vcc
	v_cndmask_b32_e32 v3, v3, v1, vcc
	v_cndmask_b32_e64 v2, v2, 16, vcc
	v_cndmask_b32_e32 v1, v1, v144, vcc
	s_cmp_eq_u32 s8, 16
	s_cbranch_scc1 .Ltopk_done
	v_cmp_gt_f32_e64 s[4:5], v145, v3
	v_cmp_gt_f32_e32 vcc, v145, v1
	s_nop 0
	v_cndmask_b32_e64 v4, v4, 17, s[4:5]
	v_cndmask_b32_e64 v3, v3, v145, s[4:5]
	v_cndmask_b32_e32 v4, v4, v2, vcc
	v_cndmask_b32_e32 v3, v3, v1, vcc
	v_cndmask_b32_e64 v2, v2, 17, vcc
	v_cndmask_b32_e32 v1, v1, v145, vcc
	s_cmp_eq_u32 s8, 17
	s_cbranch_scc1 .Ltopk_done
; DI void nsa_attn_phase(const int tid0, LAS unsigned char* lds, const P& p, int G, int c) {
;     ...
;         if (tid < 64) { unsigned mask;
;             if (i <= 3) mask = (1u << (i + 1)) - 1u;
;             else { float v1 = -1.f, v2 = -1.f; int n1 = 0, n2 = 0;
;                 for (int n = 1; n < i; ++n) { const float v = ((imp4[(0 * 64 + tid) * 33 + n] + imp4[(1 * 64 + tid) * 33 + n]) + imp4[(2 * 64 + tid) * 33 + n]) + imp4[(3 * 64 + tid) * 33 + n];
;                     if (v > v1) { v2 = v1; n2 = n1; v1 = v; n1 = n; } else if (v > v2) { v2 = v; n2 = n; } }
;                 mask = 1u | (1u << i) | (1u << n1) | (1u << n2); }
;             selm[tid] = mask; }
	v_cmp_gt_f32_e64 s[4:5], v146, v3
	v_cmp_gt_f32_e32 vcc, v146, v1
	s_nop 0
	v_cndmask_b32_e64 v4, v4, 18, s[4:5]
	v_cndmask_b32_e64 v3, v3, v146, s[4:5]
	v_cndmask_b32_e32 v4, v4, v2, vcc
	v_cndmask_b32_e32 v3, v3, v1, vcc
	v_cndmask_b32_e64 v2, v2, 18, vcc
	v_cndmask_b32_e32 v1, v1, v146, vcc
	s_cmp_eq_u32 s8, 18
	s_cbranch_scc1 .Ltopk_done
	s_waitcnt lgkmcnt(6)
	v_add_f32_e32 v144, v114, v115
	v_add_f32_e32 v145, v118, v119
	v_add_f32_e32 v146, v122, v123
	v_add_f32_e32 v144, v144, v116
	v_add_f32_e32 v145, v145, v120
	v_add_f32_e32 v146, v146, v124
	v_add_f32_e32 v144, v144, v117
	v_add_f32_e32 v145, v145, v121
	v_add_f32_e32 v146, v146, v125
	v_add_u32_e32 v138, 96, v0
	ds_read2st64_b32 v[114:115], v138 offset1:33
	ds_read2st64_b32 v[116:117], v138 offset0:66 offset1:99
	v_add_u32_e32 v139, 100, v0
	ds_read2st64_b32 v[118:119], v139 offset1:33
	ds_read2st64_b32 v[120:121], v139 offset0:66 offset1:99
	v_add_u32_e32 v140, 104, v0
	ds_read2st64_b32 v[122:123], v140 offset1:33
	ds_read2st64_b32 v[124:125], v140 offset0:66 offset1:99
	v_cmp_gt_f32_e64 s[4:5], v144, v3
	v_cmp_gt_f32_e32 vcc, v144, v1
	s_nop 0
	v_cndmask_b32_e64 v4, v4, 19, s[4:5]
	v_cndmask_b32_e64 v3, v3, v144, s[4:5]
	v_cndmask_b32_e32 v4, v4, v2, vcc
	v_cndmask_b32_e32 v3, v3, v1, vcc
	v_cndmask_b32_e64 v2, v2, 19, vcc
	v_cndmask_b32_e32 v1, v1, v144, vcc
	s_cmp_eq_u32 s8, 19
	s_cbranch_scc1 .Ltopk_done
	v_cmp_gt_f32_e64 s[4:5], v145, v3
	v_cmp_gt_f32_e32 vcc, v145, v1
	s_nop 0
	v_cndmask_b32_e64 v4, v4, 20, s[4:5]
	v_cndmask_b32_e64 v3, v3, v145, s[4:5]
	v_cndmask_b32_e32 v4, v4, v2, vcc
	v_cndmask_b32_e32 v3, v3, v1, vcc
	v_cndmask_b32_e64 v2, v2, 20, vcc
	v_cndmask_b32_e32 v1, v1, v145, vcc
	s_cmp_eq_u32 s8, 20
	s_cbranch_scc1 .Ltopk_done
	v_cmp_gt_f32_e64 s[4:5], v146, v3
	v_cmp_gt_f32_e32 vcc, v146, v1
	s_nop 0
	v_cndmask_b32_e64 v4, v4, 21, s[4:5]
	v_cndmask_b32_e64 v3, v3, v146, s[4:5]
	v_cndmask_b32_e32 v4, v4, v2, vcc
	v_cndmask_b32_e32 v3, v3, v1, vcc
	v_cndmask_b32_e64 v2, v2, 21, vcc
	v_cndmask_b32_e32 v1, v1, v146, vcc
	s_cmp_eq_u32 s8, 21
	s_cbranch_scc1 .Ltopk_done
	s_waitcnt lgkmcnt(6)
	v_add_f32_e32 v144, v126, v127
	v_add_f32_e32 v145, v130, v131
	v_add_f32_e32 v146, v134, v135
	v_add_f32_e32 v144, v144, v128
	v_add_f32_e32 v145, v145, v132
	v_add_f32_e32 v146, v146, v136
	v_add_f32_e32 v144, v144, v129
	v_add_f32_e32 v145, v145, v133
	v_add_f32_e32 v146, v146, v137
	v_add_u32_e32 v138, 108, v0
	ds_read2st64_b32 v[126:127], v138 offset1:33
	ds_read2st64_b32 v[128:129], v138 offset0:66 offset1:99
	v_add_u32_e32 v139, 112, v0
	ds_read2st64_b32 v[130:131], v139 offset1:33
	ds_read2st64_b32 v[132:133], v139 offset0:66 offset1:99
	v_add_u32_e32 v140, 116, v0
	ds_read2st64_b32 v[134:135], v140 offset1:33
	ds_read2st64_b32 v[136:137], v140 offset0:66 offset1:99
	v_cmp_gt_f32_e64 s[4:5], v144, v3
	v_cmp_gt_f32_e32 vcc, v144, v1
	s_nop 0
	v_cndmask_b32_e64 v4, v4, 22, s[4:5]
	v_cndmask_b32_e64 v3, v3, v144, s[4:5]
	v_cndmask_b32_e32 v4, v4, v2, vcc
	v_cndmask_b32_e32 v3, v3, v1, vcc
	v_cndmask_b32_e64 v2, v2, 22, vcc
	v_cndmask_b32_e32 v1, v1, v144, vcc
	s_cmp_eq_u32 s8, 22
	s_cbranch_scc1 .Ltopk_done
	v_cmp_gt_f32_e64 s[4:5], v145, v3
	v_cmp_gt_f32_e32 vcc, v145, v1
	s_nop 0
	v_cndmask_b32_e64 v4, v4, 23, s[4:5]
	v_cndmask_b32_e64 v3, v3, v145, s[4:5]
	v_cndmask_b32_e32 v4, v4, v2, vcc
	v_cndmask_b32_e32 v3, v3, v1, vcc
	v_cndmask_b32_e64 v2, v2, 23, vcc
	v_cndmask_b32_e32 v1, v1, v145, vcc
	s_cmp_eq_u32 s8, 23
	s_cbranch_scc1 .Ltopk_done
	v_cmp_gt_f32_e64 s[4:5], v146, v3
	v_cmp_gt_f32_e32 vcc, v146, v1
	s_nop 0
	v_cndmask_b32_e64 v4, v4, 24, s[4:5]
	v_cndmask_b32_e64 v3, v3, v146, s[4:5]
	v_cndmask_b32_e32 v4, v4, v2, vcc
	v_cndmask_b32_e32 v3, v3, v1, vcc
	v_cndmask_b32_e64 v2, v2, 24, vcc
	v_cndmask_b32_e32 v1, v1, v146, vcc
	s_cmp_eq_u32 s8, 24
	s_cbranch_scc1 .Ltopk_done
	s_waitcnt lgkmcnt(6)
	v_add_f32_e32 v144, v114, v115
	v_add_f32_e32 v145, v118, v119
	v_add_f32_e32 v146, v122, v123
	v_add_f32_e32 v144, v144, v116
	v_add_f32_e32 v145, v145, v120
	v_add_f32_e32 v146, v146, v124
	v_add_f32_e32 v144, v144, v117
	v_add_f32_e32 v145, v145, v121
	v_add_f32_e32 v146, v146, v125
	v_cmp_gt_f32_e64 s[4:5], v144, v3
	v_cmp_gt_f32_e32 vcc, v144, v1
	s_nop 0
	v_cndmask_b32_e64 v4, v4, 25, s[4:5]
	v_cndmask_b32_e64 v3, v3, v144, s[4:5]
	v_cndmask_b32_e32 v4, v4, v2, vcc
	v_cndmask_b32_e32 v3, v3, v1, vcc
	v_cndmask_b32_e64 v2, v2, 25, vcc
	v_cndmask_b32_e32 v1, v1, v144, vcc
	s_cmp_eq_u32 s8, 25
	s_cbranch_scc1 .Ltopk_done
	v_cmp_gt_f32_e64 s[4:5], v145, v3
	v_cmp_gt_f32_e32 vcc, v145, v1
	s_nop 0
	v_cndmask_b32_e64 v4, v4, 26, s[4:5]
	v_cndmask_b32_e64 v3, v3, v145, s[4:5]
	v_cndmask_b32_e32 v4, v4, v2, vcc
	v_cndmask_b32_e32 v3, v3, v1, vcc
	v_cndmask_b32_e64 v2, v2, 26, vcc
	v_cndmask_b32_e32 v1, v1, v145, vcc
	s_cmp_eq_u32 s8, 26
	s_cbranch_scc1 .Ltopk_done
	v_cmp_gt_f32_e64 s[4:5], v146, v3
	v_cmp_gt_f32_e32 vcc, v146, v1
	s_nop 0
	v_cndmask_b32_e64 v4, v4, 27, s[4:5]
	v_cndmask_b32_e64 v3, v3, v146, s[4:5]
	v_cndmask_b32_e32 v4, v4, v2, vcc
	v_cndmask_b32_e32 v3, v3, v1, vcc
	v_cndmask_b32_e64 v2, v2, 27, vcc
	v_cndmask_b32_e32 v1, v1, v146, vcc
	s_cmp_eq_u32 s8, 27
	s_cbranch_scc1 .Ltopk_done
	s_waitcnt lgkmcnt(0)
	v_add_f32_e32 v144, v126, v127
	v_add_f32_e32 v145, v130, v131
	v_add_f32_e32 v146, v134, v135
	v_add_f32_e32 v144, v144, v128
	v_add_f32_e32 v145, v145, v132
	v_add_f32_e32 v146, v146, v136
	v_add_f32_e32 v144, v144, v129
	v_add_f32_e32 v145, v145, v133
	v_add_f32_e32 v146, v146, v137
	v_cmp_gt_f32_e64 s[4:5], v144, v3
	v_cmp_gt_f32_e32 vcc, v144, v1
	s_nop 0
	v_cndmask_b32_e64 v4, v4, 28, s[4:5]
	v_cndmask_b32_e64 v3, v3, v144, s[4:5]
	v_cndmask_b32_e32 v4, v4, v2, vcc
	v_cndmask_b32_e32 v3, v3, v1, vcc
	v_cndmask_b32_e64 v2, v2, 28, vcc
	v_cndmask_b32_e32 v1, v1, v144, vcc
	s_cmp_eq_u32 s8, 28
	s_cbranch_scc1 .Ltopk_done
	v_cmp_gt_f32_e64 s[4:5], v145, v3
	v_cmp_gt_f32_e32 vcc, v145, v1
	s_nop 0
	v_cndmask_b32_e64 v4, v4, 29, s[4:5]
	v_cndmask_b32_e64 v3, v3, v145, s[4:5]
	v_cndmask_b32_e32 v4, v4, v2, vcc
	v_cndmask_b32_e32 v3, v3, v1, vcc
	v_cndmask_b32_e64 v2, v2, 29, vcc
	v_cndmask_b32_e32 v1, v1, v145, vcc
	s_cmp_eq_u32 s8, 29
	s_cbranch_scc1 .Ltopk_done
	v_cmp_gt_f32_e64 s[4:5], v146, v3
	v_cmp_gt_f32_e32 vcc, v146, v1
	s_nop 0
	v_cndmask_b32_e64 v4, v4, 30, s[4:5]
	v_cndmask_b32_e64 v3, v3, v146, s[4:5]
	v_cndmask_b32_e32 v4, v4, v2, vcc
	v_cndmask_b32_e32 v3, v3, v1, vcc
	v_cndmask_b32_e64 v2, v2, 30, vcc
	v_cndmask_b32_e32 v1, v1, v146, vcc
.Ltopk_done:
	v_mov_b32_e32 v6, v2
	v_mov_b32_e32 v7, v4
	s_branch .LBB0_230
